# v2 + FOX attention: counted vmcnt(7..4) at the K/V LDS writes so the two-tiles-ahead prefetch stays in flight (hipcc had drained it with vmcnt(0))
# speedup vs baseline: 1.0110x; 1.0001x over previous
.LBB0_497:
	s_andn2_b64 vcc, exec, s[28:29]
	s_cbranch_vccnz .Lfox_even_drain
	s_waitcnt vmcnt(7)
	ds_write_b128 v170, v[132:135] offset:49152
	s_waitcnt vmcnt(6)
	ds_write_b128 v170, v[136:139] offset:57344
	s_waitcnt vmcnt(5)
	ds_write_b128 v171, v[140:143] offset:16384
	s_waitcnt vmcnt(4)
	ds_write_b128 v172, v[144:147] offset:16384
	s_branch .Lfox_even_join

.Lfox_even_join:
	s_and_saveexec_b64 s[4:5], s[38:39]
	v_mul_f32_e32 v68, 0xbfb8aa3b, v169
	ds_write_b32 v189, v68
	s_or_b64 exec, exec, s[4:5]
	s_cmp_gt_u32 s30, s24
	s_waitcnt lgkmcnt(0)
	s_barrier
	s_cbranch_scc0 .LBB0_502
	s_add_i32 s4, s30, 1
	s_cmp_lt_i32 s4, s25
	s_cbranch_scc0 .LBB0_505

.LBB0_512:
	s_cmp_gt_u32 s30, s24
	s_cbranch_scc1 .Lfox_odd_drain
	s_waitcnt vmcnt(7)
	ds_write_b128 v170, v[148:151] offset:32768
	s_waitcnt vmcnt(6)
	ds_write_b128 v170, v[152:155] offset:40960
	s_waitcnt vmcnt(5)
	ds_write_b128 v171, v[156:159]
	s_waitcnt vmcnt(4)
	ds_write_b128 v172, v[160:163]
	s_branch .Lfox_odd_join
.Lfox_odd_drain:
	s_waitcnt vmcnt(3)
	ds_write_b128 v170, v[148:151] offset:32768
	s_waitcnt vmcnt(2)
	ds_write_b128 v170, v[152:155] offset:40960
	s_waitcnt vmcnt(1)
	ds_write_b128 v171, v[156:159]
	s_waitcnt vmcnt(0)
	ds_write_b128 v172, v[160:163]
.Lfox_odd_join:
	s_and_saveexec_b64 s[4:5], s[38:39]
	v_mul_f32_e32 v68, 0xbfb8aa3b, v195
	ds_write_b32 v192, v68
	s_or_b64 exec, exec, s[4:5]
